# XCD-local barriers (no L2 writeback, no top-level counter) for the 8 barriers after P3 when workgroup placement is verified group-uniform at runtime
# speedup vs baseline: 1.0299x; 1.0299x over previous
_Z4mega5MArgs:
	v_lshl_add_u32 v1, v0, 2, 0
	v_add_u32_e32 v1, 0x20000, v1
	v_mov_b32_e32 v2, 0
	ds_write2st64_b32 v1, v2, v2 offset1:8
	ds_write2st64_b32 v1, v2, v2 offset0:16 offset1:24
	v_or_b32_e32 v1, 0x800, v0
	s_mov_b64 s[4:5], -1
	s_and_saveexec_b64 s[6:7], s[4:5]
	v_lshl_add_u32 v3, v1, 2, 0
	v_add_u32_e32 v3, 0x20000, v3
	ds_write_b32 v3, v2
	s_or_b64 exec, exec, s[6:7]
	s_and_saveexec_b64 s[6:7], s[4:5]
	s_add_i32 s3, 0, 0x20000
	v_lshl_add_u32 v1, v1, 2, s3
	v_mov_b32_e32 v2, 0
	ds_write_b32 v1, v2 offset:2048
	s_or_b64 exec, exec, s[6:7]
	v_or_b32_e32 v1, 0xc00, v0
	v_cmp_gt_u32_e64 s[4:5], 7, 6
	v_cmp_gt_u32_e64 s[8:9], 7, 5
	s_and_saveexec_b64 s[6:7], s[8:9]
	v_lshl_add_u32 v2, v1, 2, 0
	v_add_u32_e32 v2, 0x20000, v2
	v_mov_b32_e32 v3, 0
	ds_write_b32 v2, v3
	s_or_b64 exec, exec, s[6:7]
	s_and_saveexec_b64 s[6:7], s[4:5]
	s_add_i32 s3, 0, 0x20000
	v_lshl_add_u32 v1, v1, 2, s3
	v_mov_b32_e32 v2, 0
	ds_write_b32 v1, v2 offset:2048
	s_or_b64 exec, exec, s[6:7]
	s_waitcnt lgkmcnt(0)
	s_barrier
	s_load_dwordx2 s[34:35], s[0:1], 0xa0
	s_getreg_b32 s3, hwreg(HW_REG_XCC_ID, 0, 4)
	v_readfirstlane_b32 s33, v0
	v_cmp_eq_u32_e64 s[10:11], 0, v0
	s_waitcnt lgkmcnt(0)
	s_add_u32 s52, s34, 0x4000
	s_addc_u32 s53, s35, 0
	s_and_b32 s3, s3, 15
	s_and_saveexec_b64 s[4:5], s[10:11]
	s_cbranch_execz .LBB0_11
	s_mov_b64 s[6:7], exec
	v_mbcnt_lo_u32_b32 v0, s6, 0
	v_mbcnt_hi_u32_b32 v0, s7, v0
	v_cmp_eq_u32_e32 vcc, 0, v0
	s_and_b64 s[8:9], exec, vcc
	s_mov_b64 exec, s[8:9]
	s_cbranch_execz .LBB0_11
	s_lshl_b32 s8, s3, 8
	s_bcnt1_i32_b64 s6, s[6:7]
	v_mov_b32_e32 v0, s8
	v_mov_b32_e32 v1, s6
	global_atomic_add v0, v1, s[52:53] offset:1024
	s_and_b32 s8, s2, 7
	s_lshl_b32 s8, s8, 8
	s_add_u32 s8, s8, 0xc000
	v_mov_b32_e32 v0, s8
	v_mov_b32_e32 v1, s3
	global_atomic_umax v0, v1, s[52:53]
	v_sub_u32_e32 v1, 15, v1
	global_atomic_umax v0, v1, s[52:53] offset:128

.LBB0_307:
	s_or_b64 exec, exec, s[4:5]
	s_andn2_b32 s33, s33, 63
	s_mov_b64 s[4:5], s[0:1]
	s_mov_b32 s58, s2
	s_waitcnt lgkmcnt(0)
	s_barrier
	v_mbcnt_lo_u32_b32 v0, -1, 0
	v_mbcnt_hi_u32_b32 v0, -1, v0
	v_and_b32_e32 v1, 7, v0
	v_lshlrev_b32_e32 v1, 8, v1
	v_and_b32_e32 v2, 8, v0
	v_lshl_add_u32 v1, v2, 4, v1
	v_add_u32_e32 v1, 0xc000, v1
	global_load_dword v2, v1, s[52:53] sc1
	s_mov_b32 s98, 1
	s_waitcnt vmcnt(0)
	v_readlane_b32 s8, v2, 0
	v_readlane_b32 s9, v2, 8
	s_nop 3
	s_add_u32 s8, s8, s9
	s_cmp_eq_u32 s8, 15
	s_cselect_b32 s98, s98, 0
	v_readlane_b32 s8, v2, 1
	v_readlane_b32 s9, v2, 9
	s_nop 3
	s_add_u32 s8, s8, s9
	s_cmp_eq_u32 s8, 15
	s_cselect_b32 s98, s98, 0
	v_readlane_b32 s8, v2, 2
	v_readlane_b32 s9, v2, 10
	s_nop 3
	s_add_u32 s8, s8, s9
	s_cmp_eq_u32 s8, 15
	s_cselect_b32 s98, s98, 0
	v_readlane_b32 s8, v2, 3
	v_readlane_b32 s9, v2, 11
	s_nop 3
	s_add_u32 s8, s8, s9
	s_cmp_eq_u32 s8, 15
	s_cselect_b32 s98, s98, 0
	v_readlane_b32 s8, v2, 4
	v_readlane_b32 s9, v2, 12
	s_nop 3
	s_add_u32 s8, s8, s9
	s_cmp_eq_u32 s8, 15
	s_cselect_b32 s98, s98, 0
	v_readlane_b32 s8, v2, 5
	v_readlane_b32 s9, v2, 13
	s_nop 3
	s_add_u32 s8, s8, s9
	s_cmp_eq_u32 s8, 15
	s_cselect_b32 s98, s98, 0
	v_readlane_b32 s8, v2, 6
	v_readlane_b32 s9, v2, 14
	s_nop 3
	s_add_u32 s8, s8, s9
	s_cmp_eq_u32 s8, 15
	s_cselect_b32 s98, s98, 0
	v_readlane_b32 s8, v2, 7
	v_readlane_b32 s9, v2, 15
	s_nop 3
	s_add_u32 s8, s8, s9
	s_cmp_eq_u32 s8, 15
	s_cselect_b32 s98, s98, 0
	v_mbcnt_lo_u32_b32 v8, -1, 0
	v_mbcnt_hi_u32_b32 v8, -1, v8
	s_cmpk_lt_i32 s58, 0xc00
	v_add_u32_e32 v0, s33, v8
	s_cselect_b64 s[6:7], -1, 0
	s_cmpk_gt_i32 s58, 0xbff
	v_readfirstlane_b32 s18, v0
	s_cbranch_scc1 .LBB0_309
	s_ashr_i32 s8, s58, 31
	s_lshr_b32 s8, s8, 29
	s_add_i32 s8, s58, s8
	s_ashr_i32 s9, s8, 3
	s_and_b32 s8, s8, -8
	s_sub_i32 s8, s58, s8
	s_cmp_lt_i32 s8, 0
	s_movk_i32 s12, 0x181
	s_cselect_b32 s12, s12, 0x180
	s_mul_i32 s8, s12, s8
	s_add_i32 s8, s8, s9
	s_mul_hi_i32 s9, s8, 0x2aaaaaab
	s_lshr_b32 s12, s9, 31
	s_ashr_i32 s9, s9, 5
	s_add_i32 s9, s9, s12
	s_lshl_b32 s12, s9, 3
	s_mulk_i32 s9, 0xc0
	s_sub_i32 s8, s8, s9
	s_bfe_u32 s9, s8, 0x3001c
	s_add_i32 s9, s8, s9
	s_and_b32 s13, s9, 0xfff8
	s_sub_i32 s8, s8, s13
	s_sext_i32_i16 s8, s8
	s_add_i32 s54, s12, s8
	s_sext_i32_i16 s8, s9
	s_ashr_i32 s8, s8, 3
	s_sub_i32 s8, 23, s8
	s_and_b32 s16, s8, 0xffff

.LBB0_653:
	s_andn2_saveexec_b64 s[8:9], s[8:9]
	s_cbranch_execz .LBB0_673
	s_mov_b64 s[8:9], exec
	s_waitcnt lgkmcnt(0)
	s_cmp_lg_u32 s98, 0
	s_cbranch_scc1 .Lfastbar_3
	buffer_wbl2 sc1
	s_waitcnt lgkmcnt(0)
	s_waitcnt vmcnt(0)
	v_mbcnt_lo_u32_b32 v1, s8, 0
	v_mbcnt_hi_u32_b32 v1, s9, v1
	v_cmp_eq_u32_e32 vcc, 0, v1
	s_and_saveexec_b64 s[12:13], vcc
	s_cbranch_execz .LBB0_656
	s_bcnt1_i32_b64 s8, s[8:9]
	v_mov_b32_e32 v2, 0x7000
	v_mov_b32_e32 v3, s8
	global_atomic_add v2, v2, v3, s[34:35] offset:1024 sc0

.Lfastbar_3:
	s_mov_b64 s[8:9], exec
	v_mbcnt_lo_u32_b32 v0, s8, 0
	v_mbcnt_hi_u32_b32 v0, s9, v0
	v_cmp_eq_u32_e32 vcc, 0, v0
	s_waitcnt vmcnt(0)
	buffer_inv sc1
	s_and_saveexec_b64 s[12:13], vcc
	s_cbranch_execz .LBB0_672
	s_bcnt1_i32_b64 s8, s[8:9]
	v_mov_b32_e32 v0, 0x2000
	v_mov_b32_e32 v1, s8
	global_atomic_add v0, v1, s[6:7] offset:1024

.LBB0_1269:
	s_andn2_saveexec_b64 s[8:9], s[8:9]
	s_cbranch_execz .LBB0_1289
	s_mov_b64 s[8:9], exec
	s_waitcnt lgkmcnt(0)
	s_cmp_lg_u32 s98, 0
	s_cbranch_scc1 .Lfastbar_10
	buffer_wbl2 sc1
	s_waitcnt lgkmcnt(0)
	s_waitcnt vmcnt(0)
	v_mbcnt_lo_u32_b32 v1, s8, 0
	v_mbcnt_hi_u32_b32 v1, s9, v1
	v_cmp_eq_u32_e32 vcc, 0, v1
	s_and_saveexec_b64 s[10:11], vcc
	s_cbranch_execz .LBB0_1272
	s_bcnt1_i32_b64 s3, s[8:9]
	v_mov_b32_e32 v2, 0x7000
	v_mov_b32_e32 v3, s3
	global_atomic_add v2, v2, v3, s[34:35] offset:1024 sc0

.Lfastbar_10:
	s_mov_b64 s[8:9], exec
	v_mbcnt_lo_u32_b32 v0, s8, 0
	v_mbcnt_hi_u32_b32 v0, s9, v0
	v_cmp_eq_u32_e32 vcc, 0, v0
	s_waitcnt vmcnt(0)
	buffer_inv sc1
	s_and_saveexec_b64 s[10:11], vcc
	s_cbranch_execz .LBB0_1288
	s_bcnt1_i32_b64 s3, s[8:9]
	v_mov_b32_e32 v0, 0x2000
	v_mov_b32_e32 v1, s3
	global_atomic_add v0, v1, s[6:7] offset:1024

	.amdhsa_kernel _Z4mega5MArgs
		.amdhsa_group_segment_fixed_size 0
		.amdhsa_private_segment_fixed_size 0
		.amdhsa_kernarg_size 424
		.amdhsa_user_sgpr_count 2
		.amdhsa_user_sgpr_dispatch_ptr 0
		.amdhsa_user_sgpr_queue_ptr 0
		.amdhsa_user_sgpr_kernarg_segment_ptr 1
		.amdhsa_user_sgpr_dispatch_id 0
		.amdhsa_user_sgpr_kernarg_preload_length 0
		.amdhsa_user_sgpr_kernarg_preload_offset 0
		.amdhsa_user_sgpr_private_segment_size 0
		.amdhsa_uses_dynamic_stack 0
		.amdhsa_enable_private_segment 0
		.amdhsa_system_sgpr_workgroup_id_x 1
		.amdhsa_system_sgpr_workgroup_id_y 0
		.amdhsa_system_sgpr_workgroup_id_z 0
		.amdhsa_system_sgpr_workgroup_info 0
		.amdhsa_system_vgpr_workitem_id 0
		.amdhsa_next_free_vgpr 255
		.amdhsa_next_free_sgpr 100
		.amdhsa_accum_offset 256
		.amdhsa_reserve_vcc 1
		.amdhsa_float_round_mode_32 0
		.amdhsa_float_round_mode_16_64 0
		.amdhsa_float_denorm_mode_32 3
		.amdhsa_float_denorm_mode_16_64 3
		.amdhsa_dx10_clamp 1
		.amdhsa_ieee_mode 1
		.amdhsa_fp16_overflow 0
		.amdhsa_tg_split 0
		.amdhsa_exception_fp_ieee_invalid_op 0
		.amdhsa_exception_fp_denorm_src 0
		.amdhsa_exception_fp_ieee_div_zero 0
		.amdhsa_exception_fp_ieee_overflow 0
		.amdhsa_exception_fp_ieee_underflow 0
		.amdhsa_exception_fp_ieee_inexact 0
		.amdhsa_exception_int_div_zero 0
	.end_amdhsa_kernel

amdhsa.kernels:
  - .agpr_count:     0
    .args:
      - .offset:         0
        .size:           168
        .value_kind:     by_value
      - .offset:         168
        .size:           4
        .value_kind:     hidden_block_count_x
      - .offset:         172
        .size:           4
        .value_kind:     hidden_block_count_y
      - .offset:         176
        .size:           4
        .value_kind:     hidden_block_count_z
      - .offset:         180
        .size:           2
        .value_kind:     hidden_group_size_x
      - .offset:         182
        .size:           2
        .value_kind:     hidden_group_size_y
      - .offset:         184
        .size:           2
        .value_kind:     hidden_group_size_z
      - .offset:         186
        .size:           2
        .value_kind:     hidden_remainder_x
      - .offset:         188
        .size:           2
        .value_kind:     hidden_remainder_y
      - .offset:         190
        .size:           2
        .value_kind:     hidden_remainder_z
      - .offset:         208
        .size:           8
        .value_kind:     hidden_global_offset_x
      - .offset:         216
        .size:           8
        .value_kind:     hidden_global_offset_y
      - .offset:         224
        .size:           8
        .value_kind:     hidden_global_offset_z
      - .offset:         232
        .size:           2
        .value_kind:     hidden_grid_dims
      - .offset:         288
        .size:           4
        .value_kind:     hidden_dynamic_lds_size
    .group_segment_fixed_size: 0
    .kernarg_segment_align: 8
    .kernarg_segment_size: 424
    .language:       OpenCL C
    .language_version:
      - 2
      - 0
    .max_flat_workgroup_size: 512
    .name:           _Z4mega5MArgs
    .private_segment_fixed_size: 0
    .sgpr_count:     106
    .sgpr_spill_count: 8
    .symbol:         _Z4mega5MArgs.kd
    .uniform_work_group_size: 1
    .uses_dynamic_stack: false
    .vgpr_count:     255
    .vgpr_spill_count: 0
    .wavefront_size: 64
